# seam: L1 invalidate issued by wave 1 before the entry barrier (right after its own store drain)
# baseline (speedup 1.0000x reference)
.LBB0_409:
	s_add_i32 s70, s70, 1
	s_cmp_ge_i32 s70, s71
	s_mov_b64 s[4:5], -1
	s_waitcnt lgkmcnt(0)
	v_readlane_b32 s24, v239, 20
	v_readlane_b32 s25, v239, 19
	s_cbranch_scc1 .LBB0_10
	v_readlane_b32 s6, v240, 12
	v_readlane_b32 s7, v240, 13
	s_and_b64 vcc, exec, s[6:7]
	s_cbranch_vccz .LBB0_464
	s_getreg_b32 s3, hwreg(HW_REG_XCC_ID, 0, 4)
	s_waitcnt vmcnt(0)
	s_waitcnt vmcnt(0)
	s_movk_i32 s4, 64
	v_cmp_eq_u32_e32 vcc, s4, v210
	s_and_saveexec_b64 s[4:5], vcc
	s_cbranch_execz .Lxb_noinv
	buffer_inv sc1
.Lxb_noinv:
	s_or_b64 exec, exec, s[4:5]
	s_barrier
	v_cmp_eq_u32_e32 vcc, 0, v210
	s_and_saveexec_b64 s[4:5], vcc
	s_cbranch_execz .LBB0_463
	v_readlane_b32 s6, v240, 5
	v_readlane_b32 s7, v240, 6
	v_readlane_b32 s8, v240, 0
	s_add_i32 s101, s101, 1
	v_mov_b32_e32 v2, s101
	s_and_b32 s9, s8, 7
	s_lshl_b32 s9, s9, 8
	s_add_u32 s9, s9, 0x12000
	s_add_u32 s12, s6, s9
	s_addc_u32 s13, s7, 0
	s_lshr_b32 s9, s8, 3
	s_lshl_b32 s9, s9, 2
	v_mov_b32_e32 v3, s9
	global_store_dword v3, v2, s[12:13]
	s_and_b32 s3, s3, 15
	s_lshl_b32 s3, s3, 8
	s_cmp_eq_u32 s101, 1
	s_cbranch_scc1 .Lxb_first
	v_readlane_b32 s10, v238, 32
	v_readlane_b32 s11, v238, 33
	v_mov_b32_e32 v2, 1
	s_lshl_b32 s9, s8, 6
	s_add_u32 s9, s9, 0x4000
	s_add_u32 s14, s6, s9
	s_addc_u32 s15, s7, 0
	v_readlane_b32 s9, v238, 34
	s_branch .Lxb_have2
